# weight conversion split: phase 0 converts W_in only, jobs 2..14 converted at start of phase 1 by workgroups 64..255 (one GEMM tile fewer)
# baseline (speedup 1.0000x reference)
.LBB0_560:
	s_andn2_b64 vcc, exec, s[12:13]
	s_cbranch_vccnz .LBB0_677
	s_movk_i32 s99, 2
	s_mov_b32 s38, 0
	s_mov_b32 s4, s54
	s_cmp_lg_u32 s53, 0
	s_cbranch_scc0 .Lcv_go
	s_cmp_lt_u32 s73, 64
	s_cbranch_scc1 .LBB0_677
	s_movk_i32 s99, 15
	s_mov_b32 s38, 2
	s_sub_i32 s4, s54, 64
	s_sub_i32 s73, s73, 64
.Lcv_go:
	v_mov_b32_e32 v128, v226
	s_lshl_b32 s54, s4, 3
	s_abs_i32 s84, s54
	v_cvt_f32_u32_e32 v0, s84
	s_lshl_b32 s85, s4, 4
	s_sub_i32 s4, 0, s84
	v_ashrrev_i32_e32 v129, 6, v128
	v_rcp_iflag_f32_e32 v0, v0
	v_and_b32_e32 v139, 48, v128
	v_lshlrev_b32_e32 v138, 2, v128
	s_mov_b32 s2, 0
	v_mul_f32_e32 v0, 0x4f7ffffe, v0
	v_cvt_u32_f32_e32 v0, v0
	v_writelane_b32 v255, s66, 52
	v_lshl_add_u32 v131, s73, 3, v129
	v_and_b32_e32 v140, 60, v138
	v_readfirstlane_b32 s5, v0
	s_mul_i32 s4, s4, s5
	s_mul_hi_u32 s4, s5, s4
	s_add_i32 s89, s5, s4
	v_or_b32_e32 v141, 7, v139
	s_branch .LBB0_564
.LBB0_563:
	s_or_b64 exec, exec, s[12:13]
	s_add_i32 s2, s74, s2
	s_add_i32 s38, s38, 1
	s_cmp_eq_u32 s38, s99
	s_cbranch_scc1 .LBB0_664

.LBB0_664:
	v_readlane_b32 s73, v255, 13
	s_mov_b32 s2, s73
	s_waitcnt lgkmcnt(0)
	s_load_dwordx2 s[4:5], s[0:1], 0x168
	v_lshl_add_u32 v32, s2, 3, v129
	v_readlane_b32 s6, v255, 33
	v_readlane_b32 s7, v255, 34
	s_movk_i32 s89, 0x2000
	s_waitcnt lgkmcnt(0)
	s_mov_b32 s2, s4
	s_mov_b32 s54, s4
	s_load_dwordx2 s[4:5], s[0:1], 0x150
	v_readlane_b32 s64, v255, 50
	v_and_b32_e32 v34, 0xfc, v138
	s_lshl_b32 s8, s2, 3
	s_mov_b64 s[10:11], -1
	s_andn2_b64 vcc, exec, s[6:7]
	v_cmp_gt_i32_e64 s[6:7], s89, v32
	s_movk_i32 s74, 0x1fff
	v_readlane_b32 s75, v255, 12
	v_readlane_b32 s53, v255, 49
	v_readlane_b32 s65, v255, 51
	v_readlane_b32 s66, v255, 52
	s_cmp_eq_u32 s53, 1
	s_cbranch_scc1 .LBB0_677
	s_cbranch_vccnz .LBB0_669
	s_and_saveexec_b64 s[10:11], s[6:7]
	s_cbranch_execz .LBB0_668
	v_ashrrev_i32_e32 v33, 31, v32
	v_lshlrev_b64 v[0:1], 12, v[32:33]
	v_and_b32_e32 v2, 63, v128
	v_lshl_or_b32 v0, v2, 3, v0
	s_waitcnt lgkmcnt(0)
	v_lshl_add_u64 v[0:1], s[4:5], 0, v[0:1]
	s_mov_b64 s[6:7], 0x9640e00
	v_lshl_add_u64 v[36:37], v[0:1], 0, s[6:7]
	s_ashr_i32 s9, s8, 31
	v_lshlrev_b64 v[38:39], 13, v[32:33]
	v_lshlrev_b32_e32 v0, 4, v2
	s_movk_i32 s2, 0x1c00
	s_lshl_b64 s[6:7], s[8:9], 12
	v_or3_b32 v38, v38, v0, s2
	s_lshl_b64 s[12:13], s[8:9], 13
	s_mov_b64 s[14:15], 0
	v_lshlrev_b32_e32 v168, 2, v34
	s_load_dwordx2 s[16:17], s[0:1], 0x10
	s_waitcnt lgkmcnt(0)
	s_add_u32 s16, s16, s64
	s_addc_u32 s17, s17, s65
	global_load_dwordx4 v[88:91], v168, s[16:17]
	global_load_dwordx4 v[92:95], v168, s[16:17] offset:1024
	global_load_dwordx4 v[96:99], v168, s[16:17] offset:2048
	global_load_dwordx4 v[100:103], v168, s[16:17] offset:3072
	s_add_u32 s16, s16, 0x1000
	s_addc_u32 s17, s17, 0
	global_load_dwordx4 v[104:107], v168, s[16:17]
	global_load_dwordx4 v[108:111], v168, s[16:17] offset:1024
	global_load_dwordx4 v[112:115], v168, s[16:17] offset:2048
	global_load_dwordx4 v[116:119], v168, s[16:17] offset:3072
	v_mov_b32_e32 v33, v32
